# FF2 layer 0 X stores write-through (sc1) as well, so the grid barrier before the pooling phase has no dirty X to flush
# baseline (speedup 1.0000x reference)
.LBB0_1460:
	ds_read_b128 v[144:147], v155
	ds_read_b128 v[148:151], v155 offset:1024
	ds_read_b128 v[158:161], v155 offset:2048
	ds_read_b128 v[162:165], v155 offset:3072
	s_add_u32 s33, s52, 0x4000
	s_addc_u32 s54, s53, 0
	s_cmp_eq_u32 s86, 60
	s_cselect_b32 s58, s82, s33
	s_cselect_b32 s59, s37, s54
	s_cselect_b32 s54, s83, s84
	s_cselect_b32 s55, s35, s85
	s_add_u32 s56, s58, 0x8000
	s_addc_u32 s57, s59, 0
	v_lshl_add_u64 v[206:207], s[52:53], 0, v[138:139]
	s_add_i32 m0, s64, 0xc000
	ds_read_b128 v[166:169], v156
	ds_read_b128 v[178:181], v156 offset:1024
	ds_read_b128 v[182:185], v156 offset:2048
	ds_read_b128 v[186:189], v156 offset:3072
	ds_read_b128 v[190:193], v156 offset:4096
	ds_read_b128 v[194:197], v156 offset:5120
	ds_read_b128 v[198:201], v156 offset:6144
	ds_read_b128 v[202:205], v156 offset:7168
	global_load_lds_dwordx4 v[206:207], off
	v_lshl_add_u64 v[206:207], s[52:53], 0, v[136:137]
	s_add_i32 m0, s64, 0xe000
	s_nop 0
	global_load_lds_dwordx4 v[206:207], off
	s_waitcnt lgkmcnt(8)
	s_barrier
	s_waitcnt lgkmcnt(0)
	s_setprio 1
	s_waitcnt lgkmcnt(0)
	v_mfma_f32_16x16x32_bf16 v[124:127], v[144:147], v[166:169], v[124:127]
	v_mfma_f32_16x16x32_bf16 v[120:123], v[158:161], v[166:169], v[120:123]
	v_mfma_f32_16x16x32_bf16 v[108:111], v[144:147], v[182:185], v[108:111]
	v_mfma_f32_16x16x32_bf16 v[104:107], v[158:161], v[182:185], v[104:107]
	v_mfma_f32_16x16x32_bf16 v[92:95], v[144:147], v[190:193], v[92:95]
	v_mfma_f32_16x16x32_bf16 v[88:91], v[158:161], v[190:193], v[88:91]
	v_mfma_f32_16x16x32_bf16 v[76:79], v[144:147], v[198:201], v[76:79]
	v_mfma_f32_16x16x32_bf16 v[72:75], v[158:161], v[198:201], v[72:75]
	v_mfma_f32_16x16x32_bf16 v[124:127], v[148:151], v[178:181], v[124:127]
	v_mfma_f32_16x16x32_bf16 v[120:123], v[162:165], v[178:181], v[120:123]
	v_mfma_f32_16x16x32_bf16 v[108:111], v[148:151], v[186:189], v[108:111]
	v_mfma_f32_16x16x32_bf16 v[104:107], v[162:165], v[186:189], v[104:107]
	v_mfma_f32_16x16x32_bf16 v[92:95], v[148:151], v[194:197], v[92:95]
	v_mfma_f32_16x16x32_bf16 v[88:91], v[162:165], v[194:197], v[88:91]
	v_mfma_f32_16x16x32_bf16 v[76:79], v[148:151], v[202:205], v[76:79]
	v_mfma_f32_16x16x32_bf16 v[72:75], v[162:165], v[202:205], v[72:75]
	s_setprio 0
	s_barrier
	s_add_i32 s33, s74, s63
	v_lshl_add_u64 v[222:223], s[54:55], 0, v[132:133]
	s_mov_b32 m0, s33
	ds_read_b128 v[206:209], v157
	ds_read_b128 v[210:213], v157 offset:1024
	ds_read_b128 v[214:217], v157 offset:2048
	ds_read_b128 v[218:221], v157 offset:3072
	global_load_lds_dwordx4 v[222:223], off
	v_lshl_add_u64 v[224:225], s[54:55], 0, v[128:129]
	s_add_i32 m0, s33, 0x2000
	s_nop 0
	global_load_lds_dwordx4 v[224:225], off
	s_barrier
	s_waitcnt lgkmcnt(0)
	s_setprio 1
	s_waitcnt lgkmcnt(0)
	v_mfma_f32_16x16x32_bf16 v[116:119], v[206:209], v[166:169], v[116:119]
	v_mfma_f32_16x16x32_bf16 v[112:115], v[214:217], v[166:169], v[112:115]
	v_mfma_f32_16x16x32_bf16 v[100:103], v[206:209], v[182:185], v[100:103]
	v_mfma_f32_16x16x32_bf16 v[96:99], v[214:217], v[182:185], v[96:99]
	v_mfma_f32_16x16x32_bf16 v[84:87], v[206:209], v[190:193], v[84:87]
	v_mfma_f32_16x16x32_bf16 v[80:83], v[214:217], v[190:193], v[80:83]
	v_mfma_f32_16x16x32_bf16 v[68:71], v[206:209], v[198:201], v[68:71]
	v_mfma_f32_16x16x32_bf16 v[64:67], v[214:217], v[198:201], v[64:67]
	v_mfma_f32_16x16x32_bf16 v[116:119], v[210:213], v[178:181], v[116:119]
	v_mfma_f32_16x16x32_bf16 v[112:115], v[218:221], v[178:181], v[112:115]
	v_mfma_f32_16x16x32_bf16 v[100:103], v[210:213], v[186:189], v[100:103]
	v_mfma_f32_16x16x32_bf16 v[96:99], v[218:221], v[186:189], v[96:99]
	v_mfma_f32_16x16x32_bf16 v[84:87], v[210:213], v[194:197], v[84:87]
	v_mfma_f32_16x16x32_bf16 v[80:83], v[218:221], v[194:197], v[80:83]
	v_mfma_f32_16x16x32_bf16 v[68:71], v[210:213], v[202:205], v[68:71]
	v_mfma_f32_16x16x32_bf16 v[64:67], v[218:221], v[202:205], v[64:67]
	s_setprio 0
	s_mov_b32 m0, s64
	v_lshl_add_u64 v[226:227], s[58:59], 0, v[134:135]
	s_barrier
	ds_read_b128 v[166:169], v156 offset:16384
	ds_read_b128 v[178:181], v156 offset:17408
	ds_read_b128 v[182:185], v156 offset:18432
	ds_read_b128 v[186:189], v156 offset:19456
	ds_read_b128 v[190:193], v156 offset:20480
	ds_read_b128 v[194:197], v156 offset:21504
	ds_read_b128 v[198:201], v156 offset:22528
	ds_read_b128 v[202:205], v156 offset:23552
	global_load_lds_dwordx4 v[226:227], off
	v_lshl_add_u64 v[226:227], s[58:59], 0, v[130:131]
	s_mov_b32 m0, s65
	s_nop 0
	global_load_lds_dwordx4 v[226:227], off
	s_barrier
	s_waitcnt lgkmcnt(0)
	s_setprio 1
	s_waitcnt lgkmcnt(0)
	v_mfma_f32_16x16x32_bf16 v[60:63], v[144:147], v[166:169], v[60:63]
	v_mfma_f32_16x16x32_bf16 v[56:59], v[158:161], v[166:169], v[56:59]
	v_mfma_f32_16x16x32_bf16 v[44:47], v[144:147], v[182:185], v[44:47]
	v_mfma_f32_16x16x32_bf16 v[40:43], v[158:161], v[182:185], v[40:43]
	v_mfma_f32_16x16x32_bf16 v[28:31], v[144:147], v[190:193], v[28:31]
	v_mfma_f32_16x16x32_bf16 v[24:27], v[158:161], v[190:193], v[24:27]
	v_mfma_f32_16x16x32_bf16 v[12:15], v[144:147], v[198:201], v[12:15]
	v_mfma_f32_16x16x32_bf16 v[8:11], v[158:161], v[198:201], v[8:11]
	v_mfma_f32_16x16x32_bf16 v[60:63], v[148:151], v[178:181], v[60:63]
	v_mfma_f32_16x16x32_bf16 v[56:59], v[162:165], v[178:181], v[56:59]
	v_mfma_f32_16x16x32_bf16 v[44:47], v[148:151], v[186:189], v[44:47]
	v_mfma_f32_16x16x32_bf16 v[40:43], v[162:165], v[186:189], v[40:43]
	v_mfma_f32_16x16x32_bf16 v[28:31], v[148:151], v[194:197], v[28:31]
	v_mfma_f32_16x16x32_bf16 v[24:27], v[162:165], v[194:197], v[24:27]
	v_mfma_f32_16x16x32_bf16 v[12:15], v[148:151], v[202:205], v[12:15]
	v_mfma_f32_16x16x32_bf16 v[8:11], v[162:165], v[202:205], v[8:11]
	s_setprio 0
	s_barrier
	s_add_u32 s88, s54, 0x100000
	s_addc_u32 s89, s55, 0
	s_add_i32 s33, s75, s63
	v_lshl_add_u64 v[144:145], s[88:89], 0, v[132:133]
	s_mov_b32 m0, s33
	s_nop 0
	global_load_lds_dwordx4 v[144:145], off
	v_lshl_add_u64 v[144:145], s[88:89], 0, v[128:129]
	s_add_i32 m0, s33, 0x2000
	s_nop 0
	global_load_lds_dwordx4 v[144:145], off
	s_waitcnt vmcnt(6)
	s_barrier
	s_setprio 1
	v_mfma_f32_16x16x32_bf16 v[52:55], v[206:209], v[166:169], v[52:55]
	v_mfma_f32_16x16x32_bf16 v[48:51], v[214:217], v[166:169], v[48:51]
	v_mfma_f32_16x16x32_bf16 v[36:39], v[206:209], v[182:185], v[36:39]
	v_mfma_f32_16x16x32_bf16 v[32:35], v[214:217], v[182:185], v[32:35]
	v_mfma_f32_16x16x32_bf16 v[20:23], v[206:209], v[190:193], v[20:23]
	v_mfma_f32_16x16x32_bf16 v[16:19], v[214:217], v[190:193], v[16:19]
	v_mfma_f32_16x16x32_bf16 v[4:7], v[206:209], v[198:201], v[4:7]
	v_mfma_f32_16x16x32_bf16 v[0:3], v[214:217], v[198:201], v[0:3]
	v_mfma_f32_16x16x32_bf16 v[52:55], v[210:213], v[178:181], v[52:55]
	v_mfma_f32_16x16x32_bf16 v[48:51], v[218:221], v[178:181], v[48:51]
	v_mfma_f32_16x16x32_bf16 v[36:39], v[210:213], v[186:189], v[36:39]
	v_mfma_f32_16x16x32_bf16 v[32:35], v[218:221], v[186:189], v[32:35]
	v_mfma_f32_16x16x32_bf16 v[20:23], v[210:213], v[194:197], v[20:23]
	v_mfma_f32_16x16x32_bf16 v[16:19], v[218:221], v[194:197], v[16:19]
	v_mfma_f32_16x16x32_bf16 v[4:7], v[210:213], v[202:205], v[4:7]
	v_mfma_f32_16x16x32_bf16 v[0:3], v[218:221], v[202:205], v[0:3]
	s_setprio 0
	s_add_i32 s33, 0, 0x18000
	v_add_u32_e32 v162, s33, v153
	s_barrier
	ds_read_b128 v[144:147], v162
	ds_read_b128 v[148:151], v162 offset:1024
	ds_read_b128 v[158:161], v162 offset:2048
	ds_read_b128 v[162:165], v162 offset:3072
	s_add_u32 s58, s58, 0x4000
	s_addc_u32 s59, s59, 0
	s_mov_b32 m0, s66
	v_lshl_add_u64 v[206:207], s[58:59], 0, v[134:135]
	ds_read_b128 v[166:169], v156 offset:32768
	ds_read_b128 v[178:181], v156 offset:33792
	ds_read_b128 v[182:185], v156 offset:34816
	ds_read_b128 v[186:189], v156 offset:35840
	ds_read_b128 v[190:193], v156 offset:36864
	ds_read_b128 v[194:197], v156 offset:37888
	ds_read_b128 v[198:201], v156 offset:38912
	ds_read_b128 v[202:205], v156 offset:39936
	global_load_lds_dwordx4 v[206:207], off
	v_lshl_add_u64 v[206:207], s[58:59], 0, v[130:131]
	s_mov_b32 m0, s67
	s_nop 0
	global_load_lds_dwordx4 v[206:207], off
	s_waitcnt lgkmcnt(8)
	s_barrier
	s_waitcnt lgkmcnt(0)
	s_setprio 1
	s_waitcnt lgkmcnt(0)
	v_mfma_f32_16x16x32_bf16 v[124:127], v[144:147], v[166:169], v[124:127]
	v_mfma_f32_16x16x32_bf16 v[120:123], v[158:161], v[166:169], v[120:123]
	v_mfma_f32_16x16x32_bf16 v[108:111], v[144:147], v[182:185], v[108:111]
	v_mfma_f32_16x16x32_bf16 v[104:107], v[158:161], v[182:185], v[104:107]
	v_mfma_f32_16x16x32_bf16 v[92:95], v[144:147], v[190:193], v[92:95]
	v_mfma_f32_16x16x32_bf16 v[88:91], v[158:161], v[190:193], v[88:91]
	v_mfma_f32_16x16x32_bf16 v[76:79], v[144:147], v[198:201], v[76:79]
	v_mfma_f32_16x16x32_bf16 v[72:75], v[158:161], v[198:201], v[72:75]
	v_mfma_f32_16x16x32_bf16 v[124:127], v[148:151], v[178:181], v[124:127]
	v_mfma_f32_16x16x32_bf16 v[120:123], v[162:165], v[178:181], v[120:123]
	v_mfma_f32_16x16x32_bf16 v[108:111], v[148:151], v[186:189], v[108:111]
	v_mfma_f32_16x16x32_bf16 v[104:107], v[162:165], v[186:189], v[104:107]
	v_mfma_f32_16x16x32_bf16 v[92:95], v[148:151], v[194:197], v[92:95]
	v_mfma_f32_16x16x32_bf16 v[88:91], v[162:165], v[194:197], v[88:91]
	v_mfma_f32_16x16x32_bf16 v[76:79], v[148:151], v[202:205], v[76:79]
	v_mfma_f32_16x16x32_bf16 v[72:75], v[162:165], v[202:205], v[72:75]
	s_setprio 0
	s_barrier
	s_add_i32 s58, 0, 0x1c000
	s_add_i32 s33, s33, s63
	v_add_u32_e32 v177, s58, v153
	v_lshl_add_u64 v[222:223], v[222:223], 0, s[16:17]
	s_mov_b32 m0, s33
	ds_read_b128 v[206:209], v177
	ds_read_b128 v[210:213], v177 offset:1024
	ds_read_b128 v[214:217], v177 offset:2048
	ds_read_b128 v[218:221], v177 offset:3072
	global_load_lds_dwordx4 v[222:223], off
	v_lshl_add_u64 v[222:223], v[224:225], 0, s[16:17]
	s_add_i32 m0, s33, 0x2000
	s_nop 0
	global_load_lds_dwordx4 v[222:223], off
	s_barrier
	s_waitcnt lgkmcnt(0)
	s_setprio 1
	s_waitcnt lgkmcnt(0)
	v_mfma_f32_16x16x32_bf16 v[116:119], v[206:209], v[166:169], v[116:119]
	v_mfma_f32_16x16x32_bf16 v[112:115], v[214:217], v[166:169], v[112:115]
	v_mfma_f32_16x16x32_bf16 v[100:103], v[206:209], v[182:185], v[100:103]
	v_mfma_f32_16x16x32_bf16 v[96:99], v[214:217], v[182:185], v[96:99]
	v_mfma_f32_16x16x32_bf16 v[84:87], v[206:209], v[190:193], v[84:87]
	v_mfma_f32_16x16x32_bf16 v[80:83], v[214:217], v[190:193], v[80:83]
	v_mfma_f32_16x16x32_bf16 v[68:71], v[206:209], v[198:201], v[68:71]
	v_mfma_f32_16x16x32_bf16 v[64:67], v[214:217], v[198:201], v[64:67]
	v_mfma_f32_16x16x32_bf16 v[116:119], v[210:213], v[178:181], v[116:119]
	v_mfma_f32_16x16x32_bf16 v[112:115], v[218:221], v[178:181], v[112:115]
	v_mfma_f32_16x16x32_bf16 v[100:103], v[210:213], v[186:189], v[100:103]
	v_mfma_f32_16x16x32_bf16 v[96:99], v[218:221], v[186:189], v[96:99]
	v_mfma_f32_16x16x32_bf16 v[84:87], v[210:213], v[194:197], v[84:87]
	v_mfma_f32_16x16x32_bf16 v[80:83], v[218:221], v[194:197], v[80:83]
	v_mfma_f32_16x16x32_bf16 v[68:71], v[210:213], v[202:205], v[68:71]
	v_mfma_f32_16x16x32_bf16 v[64:67], v[218:221], v[202:205], v[64:67]
	s_setprio 0
	s_mov_b32 m0, s68
	v_lshl_add_u64 v[222:223], s[56:57], 0, v[134:135]
	s_barrier
	ds_read_b128 v[166:169], v156 offset:49152
	ds_read_b128 v[178:181], v156 offset:50176
	ds_read_b128 v[182:185], v156 offset:51200
	ds_read_b128 v[186:189], v156 offset:52224
	ds_read_b128 v[190:193], v156 offset:53248
	ds_read_b128 v[194:197], v156 offset:54272
	ds_read_b128 v[198:201], v156 offset:55296
	ds_read_b128 v[202:205], v156 offset:56320
	global_load_lds_dwordx4 v[222:223], off
	v_lshl_add_u64 v[222:223], s[56:57], 0, v[130:131]
	s_mov_b32 m0, s69
	s_nop 0
	global_load_lds_dwordx4 v[222:223], off
	s_barrier
	s_waitcnt lgkmcnt(0)
	s_setprio 1
	s_waitcnt lgkmcnt(0)
	v_mfma_f32_16x16x32_bf16 v[60:63], v[144:147], v[166:169], v[60:63]
	v_mfma_f32_16x16x32_bf16 v[56:59], v[158:161], v[166:169], v[56:59]
	v_mfma_f32_16x16x32_bf16 v[44:47], v[144:147], v[182:185], v[44:47]
	v_mfma_f32_16x16x32_bf16 v[40:43], v[158:161], v[182:185], v[40:43]
	v_mfma_f32_16x16x32_bf16 v[28:31], v[144:147], v[190:193], v[28:31]
	v_mfma_f32_16x16x32_bf16 v[24:27], v[158:161], v[190:193], v[24:27]
	v_mfma_f32_16x16x32_bf16 v[12:15], v[144:147], v[198:201], v[12:15]
	v_mfma_f32_16x16x32_bf16 v[8:11], v[158:161], v[198:201], v[8:11]
	v_mfma_f32_16x16x32_bf16 v[60:63], v[148:151], v[178:181], v[60:63]
	v_mfma_f32_16x16x32_bf16 v[56:59], v[162:165], v[178:181], v[56:59]
	v_mfma_f32_16x16x32_bf16 v[44:47], v[148:151], v[186:189], v[44:47]
	v_mfma_f32_16x16x32_bf16 v[40:43], v[162:165], v[186:189], v[40:43]
	v_mfma_f32_16x16x32_bf16 v[28:31], v[148:151], v[194:197], v[28:31]
	v_mfma_f32_16x16x32_bf16 v[24:27], v[162:165], v[194:197], v[24:27]
	v_mfma_f32_16x16x32_bf16 v[12:15], v[148:151], v[202:205], v[12:15]
	v_mfma_f32_16x16x32_bf16 v[8:11], v[162:165], v[202:205], v[8:11]
	s_setprio 0
	s_barrier
	s_add_u32 s54, s54, 0x100080
	s_addc_u32 s55, s55, 0
	s_add_i32 s33, s58, s63
	v_lshl_add_u64 v[144:145], s[54:55], 0, v[132:133]
	s_mov_b32 m0, s33
	s_nop 0
	global_load_lds_dwordx4 v[144:145], off
	v_lshl_add_u64 v[144:145], s[54:55], 0, v[128:129]
	s_add_i32 m0, s33, 0x2000
	s_nop 0
	global_load_lds_dwordx4 v[144:145], off
	s_waitcnt vmcnt(6)
	s_barrier
	s_setprio 1
	v_mfma_f32_16x16x32_bf16 v[52:55], v[206:209], v[166:169], v[52:55]
	v_mfma_f32_16x16x32_bf16 v[48:51], v[214:217], v[166:169], v[48:51]
	v_mfma_f32_16x16x32_bf16 v[36:39], v[206:209], v[182:185], v[36:39]
	v_mfma_f32_16x16x32_bf16 v[32:35], v[214:217], v[182:185], v[32:35]
	v_mfma_f32_16x16x32_bf16 v[20:23], v[206:209], v[190:193], v[20:23]
	v_mfma_f32_16x16x32_bf16 v[16:19], v[214:217], v[190:193], v[16:19]
	v_mfma_f32_16x16x32_bf16 v[4:7], v[206:209], v[198:201], v[4:7]
	v_mfma_f32_16x16x32_bf16 v[0:3], v[214:217], v[198:201], v[0:3]
	v_mfma_f32_16x16x32_bf16 v[52:55], v[210:213], v[178:181], v[52:55]
	v_mfma_f32_16x16x32_bf16 v[48:51], v[218:221], v[178:181], v[48:51]
	v_mfma_f32_16x16x32_bf16 v[36:39], v[210:213], v[186:189], v[36:39]
	v_mfma_f32_16x16x32_bf16 v[32:35], v[218:221], v[186:189], v[32:35]
	v_mfma_f32_16x16x32_bf16 v[20:23], v[210:213], v[194:197], v[20:23]
	v_mfma_f32_16x16x32_bf16 v[16:19], v[218:221], v[194:197], v[16:19]
	v_mfma_f32_16x16x32_bf16 v[4:7], v[210:213], v[202:205], v[4:7]
	v_mfma_f32_16x16x32_bf16 v[0:3], v[218:221], v[202:205], v[0:3]
	s_setprio 0
	s_add_i32 s86, s86, 2
	s_add_u32 s84, s84, 0x100
	s_addc_u32 s85, s85, 0
	s_add_u32 s52, s52, 0x10000
	s_addc_u32 s53, s53, 0
	s_cmp_gt_u32 s86, 61
	s_barrier
	s_cbranch_scc0 .LBB0_1460
	s_lshl_b32 s82, s14, 8
	v_lshl_or_b32 v145, s81, 8, v154
	v_add_u32_e32 v144, s82, v152
	v_lshlrev_b32_e32 v145, 2, v145
	s_sub_u32 s83, s82, 0x1000
	s_lshr_b32 s83, s83, 11
	s_mul_i32 s83, s83, 6
	s_add_i32 s83, s83, 11
	s_cmp_gt_i32 s14, 15
	s_cselect_b32 s83, s83, 5
	s_lshl_b32 s83, s83, 12
	s_add_u32 s48, s72, s83
	s_addc_u32 s49, s73, 0
	v_lshl_add_u32 v146, v144, 12, v145
	global_load_dwordx4 v[148:151], v145, s[48:49]
	global_load_dwordx4 v[158:161], v145, s[48:49] offset:64
	global_load_dwordx4 v[162:165], v145, s[48:49] offset:512
	global_load_dwordx4 v[166:169], v145, s[48:49] offset:576
	s_mov_b64 s[84:85], s[24:25]
	s_mov_b64 s[86:87], s[24:25]
	v_mov_b32_e32 v226, 0
	v_mov_b32_e32 v227, 0
	v_mov_b32_e32 v228, 0
	v_mov_b32_e32 v229, 0
	v_mov_b32_e32 v230, 0
	v_mov_b32_e32 v231, 0
	v_mov_b32_e32 v232, 0
	v_mov_b32_e32 v233, 0
	global_load_dwordx4 v[178:181], v146, s[84:85]
	global_load_dwordx4 v[182:185], v146, s[84:85] offset:64
	global_load_dwordx4 v[186:189], v146, s[84:85] offset:512
	global_load_dwordx4 v[190:193], v146, s[84:85] offset:576
	s_add_u32 s84, s84, 0x10000
	s_addc_u32 s85, s85, 0
	global_load_dwordx4 v[194:197], v146, s[84:85]
	global_load_dwordx4 v[198:201], v146, s[84:85] offset:64
	global_load_dwordx4 v[202:205], v146, s[84:85] offset:512
	global_load_dwordx4 v[206:209], v146, s[84:85] offset:576
	s_add_u32 s84, s84, 0x10000
	s_addc_u32 s85, s85, 0
	global_load_dwordx4 v[210:213], v146, s[84:85]
	global_load_dwordx4 v[214:217], v146, s[84:85] offset:64
	global_load_dwordx4 v[218:221], v146, s[84:85] offset:512
	global_load_dwordx4 v[222:225], v146, s[84:85] offset:576
	s_waitcnt vmcnt(11)
	v_pk_fma_f32 v[124:125], v[124:125], v[148:149], v[178:179]
	v_pk_fma_f32 v[126:127], v[126:127], v[150:151], v[180:181]
	v_fmac_f32_e32 v226, v124, v124
	v_fmac_f32_e32 v226, v125, v125
	v_fmac_f32_e32 v226, v126, v126
	v_fmac_f32_e32 v226, v127, v127
	global_store_dwordx4 v146, v[124:127], s[86:87] sc1
	s_add_u32 s84, s84, 0x10000
	s_addc_u32 s85, s85, 0
	global_load_dwordx4 v[178:181], v146, s[84:85]
	s_waitcnt vmcnt(12)
	v_pk_fma_f32 v[120:121], v[120:121], v[158:159], v[182:183]
	v_pk_fma_f32 v[122:123], v[122:123], v[160:161], v[184:185]
	v_fmac_f32_e32 v226, v120, v120
	v_fmac_f32_e32 v226, v121, v121
	v_fmac_f32_e32 v226, v122, v122
	v_fmac_f32_e32 v226, v123, v123
	global_store_dwordx4 v146, v[120:123], s[86:87] offset:64 sc1
	global_load_dwordx4 v[182:185], v146, s[84:85] offset:64
	s_waitcnt vmcnt(13)
	v_pk_fma_f32 v[116:117], v[116:117], v[162:163], v[186:187]
	v_pk_fma_f32 v[118:119], v[118:119], v[164:165], v[188:189]
	v_fmac_f32_e32 v226, v116, v116
	v_fmac_f32_e32 v226, v117, v117
	v_fmac_f32_e32 v226, v118, v118
	v_fmac_f32_e32 v226, v119, v119
	global_store_dwordx4 v146, v[116:119], s[86:87] offset:512 sc1
	global_load_dwordx4 v[186:189], v146, s[84:85] offset:512
	s_waitcnt vmcnt(14)
	v_pk_fma_f32 v[112:113], v[112:113], v[166:167], v[190:191]
	v_pk_fma_f32 v[114:115], v[114:115], v[168:169], v[192:193]
	v_fmac_f32_e32 v226, v112, v112
	v_fmac_f32_e32 v226, v113, v113
	v_fmac_f32_e32 v226, v114, v114
	v_fmac_f32_e32 v226, v115, v115
	global_store_dwordx4 v146, v[112:115], s[86:87] offset:576 sc1
	global_load_dwordx4 v[190:193], v146, s[84:85] offset:576
	s_add_u32 s86, s86, 0x10000
	s_addc_u32 s87, s87, 0
	s_waitcnt vmcnt(15)
	v_pk_fma_f32 v[108:109], v[108:109], v[148:149], v[194:195]
	v_pk_fma_f32 v[110:111], v[110:111], v[150:151], v[196:197]
	v_fmac_f32_e32 v227, v108, v108
	v_fmac_f32_e32 v227, v109, v109
	v_fmac_f32_e32 v227, v110, v110
	v_fmac_f32_e32 v227, v111, v111
	global_store_dwordx4 v146, v[108:111], s[86:87] sc1
	s_add_u32 s84, s84, 0x50000
	s_addc_u32 s85, s85, 0
	global_load_dwordx4 v[194:197], v146, s[84:85]
	s_waitcnt vmcnt(16)
	v_pk_fma_f32 v[104:105], v[104:105], v[158:159], v[198:199]
	v_pk_fma_f32 v[106:107], v[106:107], v[160:161], v[200:201]
	v_fmac_f32_e32 v227, v104, v104
	v_fmac_f32_e32 v227, v105, v105
	v_fmac_f32_e32 v227, v106, v106
	v_fmac_f32_e32 v227, v107, v107
	global_store_dwordx4 v146, v[104:107], s[86:87] offset:64 sc1
	global_load_dwordx4 v[198:201], v146, s[84:85] offset:64
	s_waitcnt vmcnt(17)
	v_pk_fma_f32 v[100:101], v[100:101], v[162:163], v[202:203]
	v_pk_fma_f32 v[102:103], v[102:103], v[164:165], v[204:205]
	v_fmac_f32_e32 v227, v100, v100
	v_fmac_f32_e32 v227, v101, v101
	v_fmac_f32_e32 v227, v102, v102
	v_fmac_f32_e32 v227, v103, v103
	global_store_dwordx4 v146, v[100:103], s[86:87] offset:512 sc1
	global_load_dwordx4 v[202:205], v146, s[84:85] offset:512
	s_waitcnt vmcnt(18)
	v_pk_fma_f32 v[96:97], v[96:97], v[166:167], v[206:207]
	v_pk_fma_f32 v[98:99], v[98:99], v[168:169], v[208:209]
	v_fmac_f32_e32 v227, v96, v96
	v_fmac_f32_e32 v227, v97, v97
	v_fmac_f32_e32 v227, v98, v98
	v_fmac_f32_e32 v227, v99, v99
	global_store_dwordx4 v146, v[96:99], s[86:87] offset:576 sc1
	global_load_dwordx4 v[206:209], v146, s[84:85] offset:576
	s_add_u32 s86, s86, 0x10000
	s_addc_u32 s87, s87, 0
	s_waitcnt vmcnt(19)
	v_pk_fma_f32 v[92:93], v[92:93], v[148:149], v[210:211]
	v_pk_fma_f32 v[94:95], v[94:95], v[150:151], v[212:213]
	v_fmac_f32_e32 v228, v92, v92
	v_fmac_f32_e32 v228, v93, v93
	v_fmac_f32_e32 v228, v94, v94
	v_fmac_f32_e32 v228, v95, v95
	global_store_dwordx4 v146, v[92:95], s[86:87] sc1
	s_add_u32 s84, s84, 0x10000
	s_addc_u32 s85, s85, 0
	global_load_dwordx4 v[210:213], v146, s[84:85]
	s_waitcnt vmcnt(20)
	v_pk_fma_f32 v[88:89], v[88:89], v[158:159], v[214:215]
	v_pk_fma_f32 v[90:91], v[90:91], v[160:161], v[216:217]
	v_fmac_f32_e32 v228, v88, v88
	v_fmac_f32_e32 v228, v89, v89
	v_fmac_f32_e32 v228, v90, v90
	v_fmac_f32_e32 v228, v91, v91
	global_store_dwordx4 v146, v[88:91], s[86:87] offset:64 sc1
	global_load_dwordx4 v[214:217], v146, s[84:85] offset:64
	s_waitcnt vmcnt(21)
	v_pk_fma_f32 v[84:85], v[84:85], v[162:163], v[218:219]
	v_pk_fma_f32 v[86:87], v[86:87], v[164:165], v[220:221]
	v_fmac_f32_e32 v228, v84, v84
	v_fmac_f32_e32 v228, v85, v85
	v_fmac_f32_e32 v228, v86, v86
	v_fmac_f32_e32 v228, v87, v87
	global_store_dwordx4 v146, v[84:87], s[86:87] offset:512 sc1
	global_load_dwordx4 v[218:221], v146, s[84:85] offset:512
	s_waitcnt vmcnt(22)
	v_pk_fma_f32 v[80:81], v[80:81], v[166:167], v[222:223]
	v_pk_fma_f32 v[82:83], v[82:83], v[168:169], v[224:225]
	v_fmac_f32_e32 v228, v80, v80
	v_fmac_f32_e32 v228, v81, v81
	v_fmac_f32_e32 v228, v82, v82
	v_fmac_f32_e32 v228, v83, v83
	global_store_dwordx4 v146, v[80:83], s[86:87] offset:576 sc1
	global_load_dwordx4 v[222:225], v146, s[84:85] offset:576
	s_add_u32 s86, s86, 0x10000
	s_addc_u32 s87, s87, 0
	s_waitcnt vmcnt(22)
	v_pk_fma_f32 v[76:77], v[76:77], v[148:149], v[178:179]
	v_pk_fma_f32 v[78:79], v[78:79], v[150:151], v[180:181]
	v_fmac_f32_e32 v229, v76, v76
	v_fmac_f32_e32 v229, v77, v77
	v_fmac_f32_e32 v229, v78, v78
	v_fmac_f32_e32 v229, v79, v79
	global_store_dwordx4 v146, v[76:79], s[86:87] sc1
	s_add_u32 s84, s84, 0x10000
	s_addc_u32 s85, s85, 0
	global_load_dwordx4 v[178:181], v146, s[84:85]
	s_waitcnt vmcnt(22)
	v_pk_fma_f32 v[72:73], v[72:73], v[158:159], v[182:183]
	v_pk_fma_f32 v[74:75], v[74:75], v[160:161], v[184:185]
	v_fmac_f32_e32 v229, v72, v72
	v_fmac_f32_e32 v229, v73, v73
	v_fmac_f32_e32 v229, v74, v74
	v_fmac_f32_e32 v229, v75, v75
	global_store_dwordx4 v146, v[72:75], s[86:87] offset:64 sc1
	global_load_dwordx4 v[182:185], v146, s[84:85] offset:64
	s_waitcnt vmcnt(22)
	v_pk_fma_f32 v[68:69], v[68:69], v[162:163], v[186:187]
	v_pk_fma_f32 v[70:71], v[70:71], v[164:165], v[188:189]
	v_fmac_f32_e32 v229, v68, v68
	v_fmac_f32_e32 v229, v69, v69
	v_fmac_f32_e32 v229, v70, v70
	v_fmac_f32_e32 v229, v71, v71
	global_store_dwordx4 v146, v[68:71], s[86:87] offset:512 sc1
	global_load_dwordx4 v[186:189], v146, s[84:85] offset:512
	s_waitcnt vmcnt(22)
	v_pk_fma_f32 v[64:65], v[64:65], v[166:167], v[190:191]
	v_pk_fma_f32 v[66:67], v[66:67], v[168:169], v[192:193]
	v_fmac_f32_e32 v229, v64, v64
	v_fmac_f32_e32 v229, v65, v65
	v_fmac_f32_e32 v229, v66, v66
	v_fmac_f32_e32 v229, v67, v67
	global_store_dwordx4 v146, v[64:67], s[86:87] offset:576 sc1
	global_load_dwordx4 v[190:193], v146, s[84:85] offset:576
	s_add_u32 s86, s86, 0x50000
	s_addc_u32 s87, s87, 0
	s_waitcnt vmcnt(22)
	v_pk_fma_f32 v[60:61], v[60:61], v[148:149], v[194:195]
	v_pk_fma_f32 v[62:63], v[62:63], v[150:151], v[196:197]
	v_fmac_f32_e32 v230, v60, v60
	v_fmac_f32_e32 v230, v61, v61
	v_fmac_f32_e32 v230, v62, v62
	v_fmac_f32_e32 v230, v63, v63
	global_store_dwordx4 v146, v[60:63], s[86:87] sc1
	s_add_u32 s84, s84, 0x10000
	s_addc_u32 s85, s85, 0
	global_load_dwordx4 v[194:197], v146, s[84:85]
	s_waitcnt vmcnt(22)
	v_pk_fma_f32 v[56:57], v[56:57], v[158:159], v[198:199]
	v_pk_fma_f32 v[58:59], v[58:59], v[160:161], v[200:201]
	v_fmac_f32_e32 v230, v56, v56
	v_fmac_f32_e32 v230, v57, v57
	v_fmac_f32_e32 v230, v58, v58
	v_fmac_f32_e32 v230, v59, v59
	global_store_dwordx4 v146, v[56:59], s[86:87] offset:64 sc1
	global_load_dwordx4 v[198:201], v146, s[84:85] offset:64
	s_waitcnt vmcnt(22)
	v_pk_fma_f32 v[52:53], v[52:53], v[162:163], v[202:203]
	v_pk_fma_f32 v[54:55], v[54:55], v[164:165], v[204:205]
	v_fmac_f32_e32 v230, v52, v52
	v_fmac_f32_e32 v230, v53, v53
	v_fmac_f32_e32 v230, v54, v54
	v_fmac_f32_e32 v230, v55, v55
	global_store_dwordx4 v146, v[52:55], s[86:87] offset:512 sc1
	global_load_dwordx4 v[202:205], v146, s[84:85] offset:512
	s_waitcnt vmcnt(22)
	v_pk_fma_f32 v[48:49], v[48:49], v[166:167], v[206:207]
	v_pk_fma_f32 v[50:51], v[50:51], v[168:169], v[208:209]
	v_fmac_f32_e32 v230, v48, v48
	v_fmac_f32_e32 v230, v49, v49
	v_fmac_f32_e32 v230, v50, v50
	v_fmac_f32_e32 v230, v51, v51
	global_store_dwordx4 v146, v[48:51], s[86:87] offset:576 sc1
	global_load_dwordx4 v[206:209], v146, s[84:85] offset:576
	s_add_u32 s86, s86, 0x10000
	s_addc_u32 s87, s87, 0
	s_waitcnt vmcnt(22)
	v_pk_fma_f32 v[44:45], v[44:45], v[148:149], v[210:211]
	v_pk_fma_f32 v[46:47], v[46:47], v[150:151], v[212:213]
	v_fmac_f32_e32 v231, v44, v44
	v_fmac_f32_e32 v231, v45, v45
	v_fmac_f32_e32 v231, v46, v46
	v_fmac_f32_e32 v231, v47, v47
	global_store_dwordx4 v146, v[44:47], s[86:87] sc1
	s_waitcnt vmcnt(21)
	v_pk_fma_f32 v[40:41], v[40:41], v[158:159], v[214:215]
	v_pk_fma_f32 v[42:43], v[42:43], v[160:161], v[216:217]
	v_fmac_f32_e32 v231, v40, v40
	v_fmac_f32_e32 v231, v41, v41
	v_fmac_f32_e32 v231, v42, v42
	v_fmac_f32_e32 v231, v43, v43
	global_store_dwordx4 v146, v[40:43], s[86:87] offset:64 sc1
	s_waitcnt vmcnt(20)
	v_pk_fma_f32 v[36:37], v[36:37], v[162:163], v[218:219]
	v_pk_fma_f32 v[38:39], v[38:39], v[164:165], v[220:221]
	v_fmac_f32_e32 v231, v36, v36
	v_fmac_f32_e32 v231, v37, v37
	v_fmac_f32_e32 v231, v38, v38
	v_fmac_f32_e32 v231, v39, v39
	global_store_dwordx4 v146, v[36:39], s[86:87] offset:512 sc1
	s_waitcnt vmcnt(19)
	v_pk_fma_f32 v[32:33], v[32:33], v[166:167], v[222:223]
	v_pk_fma_f32 v[34:35], v[34:35], v[168:169], v[224:225]
	v_fmac_f32_e32 v231, v32, v32
	v_fmac_f32_e32 v231, v33, v33
	v_fmac_f32_e32 v231, v34, v34
	v_fmac_f32_e32 v231, v35, v35
	global_store_dwordx4 v146, v[32:35], s[86:87] offset:576 sc1
	s_add_u32 s86, s86, 0x10000
	s_addc_u32 s87, s87, 0
	s_waitcnt vmcnt(18)
	v_pk_fma_f32 v[28:29], v[28:29], v[148:149], v[178:179]
	v_pk_fma_f32 v[30:31], v[30:31], v[150:151], v[180:181]
	v_fmac_f32_e32 v232, v28, v28
	v_fmac_f32_e32 v232, v29, v29
	v_fmac_f32_e32 v232, v30, v30
	v_fmac_f32_e32 v232, v31, v31
	global_store_dwordx4 v146, v[28:31], s[86:87] sc1
	s_waitcnt vmcnt(17)
	v_pk_fma_f32 v[24:25], v[24:25], v[158:159], v[182:183]
	v_pk_fma_f32 v[26:27], v[26:27], v[160:161], v[184:185]
	v_fmac_f32_e32 v232, v24, v24
	v_fmac_f32_e32 v232, v25, v25
	v_fmac_f32_e32 v232, v26, v26
	v_fmac_f32_e32 v232, v27, v27
	global_store_dwordx4 v146, v[24:27], s[86:87] offset:64 sc1
	s_waitcnt vmcnt(16)
	v_pk_fma_f32 v[20:21], v[20:21], v[162:163], v[186:187]
	v_pk_fma_f32 v[22:23], v[22:23], v[164:165], v[188:189]
	v_fmac_f32_e32 v232, v20, v20
	v_fmac_f32_e32 v232, v21, v21
	v_fmac_f32_e32 v232, v22, v22
	v_fmac_f32_e32 v232, v23, v23
	global_store_dwordx4 v146, v[20:23], s[86:87] offset:512 sc1
	s_waitcnt vmcnt(15)
	v_pk_fma_f32 v[16:17], v[16:17], v[166:167], v[190:191]
	v_pk_fma_f32 v[18:19], v[18:19], v[168:169], v[192:193]
	v_fmac_f32_e32 v232, v16, v16
	v_fmac_f32_e32 v232, v17, v17
	v_fmac_f32_e32 v232, v18, v18
	v_fmac_f32_e32 v232, v19, v19
	global_store_dwordx4 v146, v[16:19], s[86:87] offset:576 sc1
	s_add_u32 s86, s86, 0x10000
	s_addc_u32 s87, s87, 0
	s_waitcnt vmcnt(14)
	v_pk_fma_f32 v[12:13], v[12:13], v[148:149], v[194:195]
	v_pk_fma_f32 v[14:15], v[14:15], v[150:151], v[196:197]
	v_fmac_f32_e32 v233, v12, v12
	v_fmac_f32_e32 v233, v13, v13
	v_fmac_f32_e32 v233, v14, v14
	v_fmac_f32_e32 v233, v15, v15
	global_store_dwordx4 v146, v[12:15], s[86:87] sc1
	s_waitcnt vmcnt(13)
	v_pk_fma_f32 v[8:9], v[8:9], v[158:159], v[198:199]
	v_pk_fma_f32 v[10:11], v[10:11], v[160:161], v[200:201]
	v_fmac_f32_e32 v233, v8, v8
	v_fmac_f32_e32 v233, v9, v9
	v_fmac_f32_e32 v233, v10, v10
	v_fmac_f32_e32 v233, v11, v11
	global_store_dwordx4 v146, v[8:11], s[86:87] offset:64 sc1
	s_waitcnt vmcnt(12)
	v_pk_fma_f32 v[4:5], v[4:5], v[162:163], v[202:203]
	v_pk_fma_f32 v[6:7], v[6:7], v[164:165], v[204:205]
	v_fmac_f32_e32 v233, v4, v4
	v_fmac_f32_e32 v233, v5, v5
	v_fmac_f32_e32 v233, v6, v6
	v_fmac_f32_e32 v233, v7, v7
	global_store_dwordx4 v146, v[4:7], s[86:87] offset:512 sc1
	s_waitcnt vmcnt(11)
	v_pk_fma_f32 v[0:1], v[0:1], v[166:167], v[206:207]
	v_pk_fma_f32 v[2:3], v[2:3], v[168:169], v[208:209]
	v_fmac_f32_e32 v233, v0, v0
	v_fmac_f32_e32 v233, v1, v1
	v_fmac_f32_e32 v233, v2, v2
	v_fmac_f32_e32 v233, v3, v3
	global_store_dwordx4 v146, v[0:3], s[86:87] offset:576 sc1
	s_mov_b32 s81, s34
	s_mov_b64 s[52:53], s[50:51]
	s_mov_b64 s[54:55], s[40:41]
	s_mov_b32 s14, s36
	s_and_b64 vcc, exec, s[12:13]
	s_cbranch_vccz .LBB0_1457
	s_waitcnt vmcnt(0)
	s_cmpk_gt_u32 s60, 0xff
	s_cbranch_scc1 .LBB0_1464
	s_barrier
